# P1 start of odd-loc workgroups delayed ~3.4 us (anti-phase halves within an XCC)
# speedup vs baseline: 1.0045x; 1.0037x over previous
; __global__ void __launch_bounds__(512, 2) mk_fwd(Args args) {
;     ...
;             if (STAGGER_TICKS > 0) { const unsigned long long t0_ = __builtin_amdgcn_s_memrealtime(), w_ = (unsigned long long)((cid >> 3) & 3) * STAGGER_TICKS; while (__builtin_amdgcn_s_memrealtime() - t0_ < w_) __builtin_amdgcn_s_sleep(16); }
;             gemm_phase<P1Prog, true, false, false, P1_SLACK>(F.lds, 1024, P, F.wave, tg_k[0], tg_e[0]);
.Lskew_loop:
	s_sleep 110
	s_sub_u32 s98, s98, 1
	s_cmp_lg_u32 s98, 0
	s_cbranch_scc1 .Lskew_loop
